# write-through dwordx4 stores plus write-through on the 8 contiguous dwordx2 row stores of the x->bf16 copy in the first phase
# speedup vs baseline: 1.0129x; 1.0026x over previous
; __device__ __forceinline__ unsigned cvtpk(float lo, float hi) { f32x2 v = {lo, hi}; bf16x2_t b = __builtin_convertvector(v, bf16x2_t); return __builtin_bit_cast(unsigned, b); }
; __device__ __forceinline__ void p0_row(const float* xrow, bf16_t* hbrow, float* ss, int lane) {
;     ...
; #pragma unroll
;     for (int j = 0; j < 8; ++j) {
;         u32x2 w; w.x = cvtpk(v[j].x, v[j].y); w.y = cvtpk(v[j].z, v[j].w);
;         *(u32x2*)(hbrow + 4 * lane + 256 * j) = w; }
.LBB0_542:
	s_or_b64 exec, exec, s[16:17]
	s_waitcnt lgkmcnt(0)
	v_lshl_add_u64 v[46:47], s[8:9], 0, v[36:37]
	v_cvt_pk_bf16_f32 v30, v30, v31
	v_cvt_pk_bf16_f32 v31, v32, v33
	v_add_co_u32_e32 v32, vcc, 0x1af00000, v46
	v_cvt_pk_bf16_f32 v2, v2, v3
	s_nop 0
	v_addc_co_u32_e32 v33, vcc, 0, v47, vcc
	v_cvt_pk_bf16_f32 v3, v4, v5
	global_store_dwordx2 v[32:33], v[2:3], off offset:2048 sc0 sc1
	v_cvt_pk_bf16_f32 v2, v6, v7
	v_cvt_pk_bf16_f32 v3, v8, v9
	global_store_dwordx2 v[32:33], v[2:3], off offset:2560 sc0 sc1
	v_cvt_pk_bf16_f32 v2, v10, v11
	v_cvt_pk_bf16_f32 v3, v12, v13
	s_add_i32 s0, s0, s72
	v_cvt_pk_bf16_f32 v26, v26, v27
	v_cvt_pk_bf16_f32 v27, v28, v29
	v_cvt_pk_bf16_f32 v22, v22, v23
	v_cvt_pk_bf16_f32 v23, v24, v25
	v_cvt_pk_bf16_f32 v18, v18, v19
	v_cvt_pk_bf16_f32 v19, v20, v21
	global_store_dwordx2 v[32:33], v[2:3], off offset:3072 sc0 sc1
	v_cvt_pk_bf16_f32 v2, v14, v15
	v_cvt_pk_bf16_f32 v3, v16, v17
	v_lshl_add_u64 v[34:35], v[34:35], 0, s[10:11]
	v_lshl_add_u64 v[36:37], v[36:37], 0, s[12:13]
	s_cmpk_gt_i32 s0, 0x1fff
	v_lshl_add_u64 v[38:39], v[38:39], 0, s[14:15]
	global_store_dwordx2 v[32:33], v[30:31], off sc0 sc1
	global_store_dwordx2 v[32:33], v[26:27], off offset:512 sc0 sc1
	global_store_dwordx2 v[32:33], v[22:23], off offset:1024 sc0 sc1
	global_store_dwordx2 v[32:33], v[18:19], off offset:1536 sc0 sc1
	global_store_dwordx2 v[32:33], v[2:3], off offset:3584 sc0 sc1
	s_cbranch_scc1 .LBB0_545
